# k48 + the w_out epilogue stores the residual stream h (re-read by the FF2 epilogue) without the non-temporal hint
# speedup vs baseline: 1.0137x; 1.0137x over previous
.LBB0_754:
	s_or_b64 exec, exec, s[12:13]
	v_mov_b32_e32 v128, s22
	v_mov_b32_e32 v129, s23
	s_waitcnt lgkmcnt(0)
	s_barrier
	v_lshl_add_u64 v[152:153], v[200:201], 2, v[128:129]
	ds_read_b32 v158, v209 offset:8192
	v_lshlrev_b64 v[144:145], 10, v[144:145]
	s_add_u32 s8, s18, 0x29d00000
	v_lshl_add_u64 v[160:161], v[144:145], 0, v[200:201]
	s_addc_u32 s9, s19, 0
	v_cvt_pk_bf16_f32 v154, v112, v113
	v_cvt_pk_bf16_f32 v155, v114, v115
	v_cvt_pk_bf16_f32 v156, v116, v117
	v_lshlrev_b64 v[160:161], 1, v[160:161]
	s_waitcnt lgkmcnt(0)
	v_pk_mul_f32 v[114:115], v[114:115], v[158:159] op_sel_hi:[1,0]
	v_pk_mul_f32 v[112:113], v[112:113], v[158:159] op_sel_hi:[1,0]
	v_pk_mul_f32 v[116:117], v[116:117], v[158:159] op_sel_hi:[1,0]
	v_cvt_pk_bf16_f32 v157, v118, v119
	v_lshl_add_u64 v[168:169], s[8:9], 0, v[160:161]
	v_pk_mul_f32 v[118:119], v[118:119], v[158:159] op_sel_hi:[1,0]
	global_store_dwordx4 v[168:169], v[154:157], off
	v_lshlrev_b64 v[150:151], 10, v[150:151]
	s_add_u32 s10, s18, 0x12300000
	v_lshl_add_u64 v[162:163], v[150:151], 0, v[200:201]
	s_addc_u32 s11, s19, 0
	v_lshlrev_b64 v[162:163], 1, v[162:163]
	v_lshl_add_u64 v[154:155], s[10:11], 0, v[160:161]
	v_lshl_add_u64 v[170:171], s[8:9], 0, v[162:163]
	v_lshlrev_b64 v[148:149], 10, v[148:149]
	v_lshl_add_u64 v[164:165], v[148:149], 0, v[200:201]
	v_lshl_add_u64 v[156:157], s[10:11], 0, v[162:163]
	v_lshlrev_b64 v[164:165], 1, v[164:165]
	v_lshl_add_u64 v[172:173], s[8:9], 0, v[164:165]
	v_lshlrev_b64 v[146:147], 10, v[146:147]
	v_lshl_add_u64 v[166:167], v[146:147], 0, v[200:201]
	v_lshlrev_b64 v[166:167], 1, v[166:167]
	v_lshl_add_u64 v[160:161], s[10:11], 0, v[164:165]
	v_lshl_add_u64 v[174:175], s[8:9], 0, v[166:167]
	v_pk_mul_f32 v[114:115], v[242:243], v[114:115]
	v_pk_mul_f32 v[112:113], v[240:241], v[112:113]
	v_pk_mul_f32 v[116:117], v[244:245], v[116:117]
	v_pk_mul_f32 v[118:119], v[246:247], v[118:119]
	v_cvt_pk_bf16_f32 v112, v112, v113
	v_cvt_pk_bf16_f32 v113, v114, v115
	v_cvt_pk_bf16_f32 v114, v116, v117
	s_nop 0
	v_cvt_pk_bf16_f32 v115, v118, v119
	ds_read_b32 v116, v209 offset:8256
	global_store_dwordx4 v[154:155], v[112:115], off sc1
	s_waitcnt lgkmcnt(0)
	v_pk_mul_f32 v[118:119], v[126:127], v[116:117] op_sel_hi:[1,0]
	v_cvt_pk_bf16_f32 v112, v120, v121
	v_cvt_pk_bf16_f32 v113, v122, v123
	v_cvt_pk_bf16_f32 v114, v124, v125
	v_cvt_pk_bf16_f32 v115, v126, v127
	global_store_dwordx4 v[170:171], v[112:115], off
	v_pk_mul_f32 v[118:119], v[246:247], v[118:119]
	s_nop 0
	v_pk_mul_f32 v[112:113], v[122:123], v[116:117] op_sel_hi:[1,0]
	v_pk_mul_f32 v[114:115], v[120:121], v[116:117] op_sel_hi:[1,0]
	v_pk_mul_f32 v[116:117], v[124:125], v[116:117] op_sel_hi:[1,0]
	v_pk_mul_f32 v[120:121], v[242:243], v[112:113]
	v_pk_mul_f32 v[112:113], v[240:241], v[114:115]
	v_pk_mul_f32 v[114:115], v[244:245], v[116:117]
	v_cvt_pk_bf16_f32 v112, v112, v113
	v_cvt_pk_bf16_f32 v113, v120, v121
	s_nop 0
	v_cvt_pk_bf16_f32 v114, v114, v115
	v_cvt_pk_bf16_f32 v115, v118, v119
	ds_read_b32 v116, v209 offset:8320
	global_store_dwordx4 v[156:157], v[112:115], off sc1
	s_nop 1
	v_cvt_pk_bf16_f32 v112, v104, v105
	v_cvt_pk_bf16_f32 v113, v106, v107
	v_cvt_pk_bf16_f32 v114, v108, v109
	s_waitcnt lgkmcnt(0)
	v_pk_mul_f32 v[106:107], v[106:107], v[116:117] op_sel_hi:[1,0]
	v_pk_mul_f32 v[104:105], v[104:105], v[116:117] op_sel_hi:[1,0]
	v_pk_mul_f32 v[108:109], v[108:109], v[116:117] op_sel_hi:[1,0]
	v_cvt_pk_bf16_f32 v115, v110, v111
	v_pk_mul_f32 v[110:111], v[110:111], v[116:117] op_sel_hi:[1,0]
	v_pk_mul_f32 v[106:107], v[242:243], v[106:107]
	v_pk_mul_f32 v[104:105], v[240:241], v[104:105]
	v_pk_mul_f32 v[108:109], v[244:245], v[108:109]
	global_store_dwordx4 v[172:173], v[112:115], off
	v_pk_mul_f32 v[110:111], v[246:247], v[110:111]
	v_cvt_pk_bf16_f32 v104, v104, v105
	v_cvt_pk_bf16_f32 v105, v106, v107
	v_cvt_pk_bf16_f32 v106, v108, v109
	s_nop 0
	v_cvt_pk_bf16_f32 v107, v110, v111
	ds_read_b32 v108, v209 offset:8384
	global_store_dwordx4 v[160:161], v[104:107], off sc1
	s_nop 1
	v_cvt_pk_bf16_f32 v104, v100, v101
	v_cvt_pk_bf16_f32 v105, v102, v103
	v_cvt_pk_bf16_f32 v106, v96, v97
	v_cvt_pk_bf16_f32 v107, v98, v99
	s_waitcnt lgkmcnt(0)
	v_pk_mul_f32 v[102:103], v[102:103], v[108:109] op_sel_hi:[1,0]
	v_pk_mul_f32 v[98:99], v[98:99], v[108:109] op_sel_hi:[1,0]
	v_pk_mul_f32 v[96:97], v[96:97], v[108:109] op_sel_hi:[1,0]
	global_store_dwordx4 v[174:175], v[104:107], off
	v_pk_mul_f32 v[100:101], v[100:101], v[108:109] op_sel_hi:[1,0]
	v_pk_mul_f32 v[102:103], v[242:243], v[102:103]
	v_pk_mul_f32 v[104:105], v[246:247], v[98:99]
	v_pk_mul_f32 v[98:99], v[244:245], v[96:97]
	v_pk_mul_f32 v[100:101], v[240:241], v[100:101]
	s_nop 0
	v_cvt_pk_bf16_f32 v96, v100, v101
	v_cvt_pk_bf16_f32 v97, v102, v103
	v_cvt_pk_bf16_f32 v98, v98, v99
	v_cvt_pk_bf16_f32 v99, v104, v105
	ds_read_b32 v102, v209 offset:8704
	v_lshl_add_u64 v[100:101], s[10:11], 0, v[166:167]
	global_store_dwordx4 v[100:101], v[96:99], off sc1
	s_nop 1
	v_lshlrev_b64 v[96:97], 10, v[142:143]
	v_lshl_add_u64 v[104:105], v[96:97], 0, v[200:201]
	v_lshlrev_b64 v[104:105], 1, v[104:105]
	v_cvt_pk_bf16_f32 v98, v92, v93
	v_cvt_pk_bf16_f32 v99, v94, v95
	v_cvt_pk_bf16_f32 v100, v88, v89
	v_cvt_pk_bf16_f32 v101, v90, v91
	v_lshl_add_u64 v[106:107], s[8:9], 0, v[104:105]
	s_waitcnt lgkmcnt(0)
	v_pk_mul_f32 v[94:95], v[94:95], v[102:103] op_sel_hi:[1,0]
	v_pk_mul_f32 v[90:91], v[90:91], v[102:103] op_sel_hi:[1,0]
	v_pk_mul_f32 v[88:89], v[88:89], v[102:103] op_sel_hi:[1,0]
	global_store_dwordx4 v[106:107], v[98:101], off
	v_pk_mul_f32 v[92:93], v[92:93], v[102:103] op_sel_hi:[1,0]
	v_pk_mul_f32 v[94:95], v[242:243], v[94:95]
	v_pk_mul_f32 v[98:99], v[246:247], v[90:91]
	v_pk_mul_f32 v[90:91], v[244:245], v[88:89]
	v_pk_mul_f32 v[92:93], v[240:241], v[92:93]
	s_nop 0
	v_cvt_pk_bf16_f32 v88, v92, v93
	v_cvt_pk_bf16_f32 v89, v94, v95
	v_cvt_pk_bf16_f32 v90, v90, v91
	v_cvt_pk_bf16_f32 v91, v98, v99
	ds_read_b32 v94, v209 offset:8768
	v_lshl_add_u64 v[92:93], s[10:11], 0, v[104:105]
	global_store_dwordx4 v[92:93], v[88:91], off sc1
	s_nop 1
	v_lshlrev_b64 v[88:89], 10, v[140:141]
	v_lshl_add_u64 v[98:99], v[88:89], 0, v[200:201]
	v_lshlrev_b64 v[98:99], 1, v[98:99]
	v_cvt_pk_bf16_f32 v90, v84, v85
	v_cvt_pk_bf16_f32 v91, v86, v87
	v_cvt_pk_bf16_f32 v92, v80, v81
	v_cvt_pk_bf16_f32 v93, v82, v83
	v_lshl_add_u64 v[100:101], s[8:9], 0, v[98:99]
	s_waitcnt lgkmcnt(0)
	v_pk_mul_f32 v[86:87], v[86:87], v[94:95] op_sel_hi:[1,0]
	v_pk_mul_f32 v[82:83], v[82:83], v[94:95] op_sel_hi:[1,0]
	v_pk_mul_f32 v[80:81], v[80:81], v[94:95] op_sel_hi:[1,0]
	global_store_dwordx4 v[100:101], v[90:93], off
	v_pk_mul_f32 v[84:85], v[84:85], v[94:95] op_sel_hi:[1,0]
	v_pk_mul_f32 v[86:87], v[242:243], v[86:87]
	v_pk_mul_f32 v[90:91], v[246:247], v[82:83]
	v_pk_mul_f32 v[82:83], v[244:245], v[80:81]
	v_pk_mul_f32 v[84:85], v[240:241], v[84:85]
	s_nop 0
	v_cvt_pk_bf16_f32 v80, v84, v85
	v_cvt_pk_bf16_f32 v81, v86, v87
	v_cvt_pk_bf16_f32 v82, v82, v83
	v_cvt_pk_bf16_f32 v83, v90, v91
	ds_read_b32 v86, v209 offset:8832
	v_lshl_add_u64 v[84:85], s[10:11], 0, v[98:99]
	global_store_dwordx4 v[84:85], v[80:83], off sc1
	s_nop 1
	v_lshlrev_b64 v[80:81], 10, v[138:139]
	v_lshl_add_u64 v[90:91], v[80:81], 0, v[200:201]
	v_lshlrev_b64 v[90:91], 1, v[90:91]
	v_cvt_pk_bf16_f32 v82, v76, v77
	v_cvt_pk_bf16_f32 v83, v78, v79
	v_cvt_pk_bf16_f32 v84, v72, v73
	v_cvt_pk_bf16_f32 v85, v74, v75
	v_lshl_add_u64 v[92:93], s[8:9], 0, v[90:91]
	s_waitcnt lgkmcnt(0)
	v_pk_mul_f32 v[78:79], v[78:79], v[86:87] op_sel_hi:[1,0]
	v_pk_mul_f32 v[74:75], v[74:75], v[86:87] op_sel_hi:[1,0]
	v_pk_mul_f32 v[72:73], v[72:73], v[86:87] op_sel_hi:[1,0]
	global_store_dwordx4 v[92:93], v[82:85], off
	v_pk_mul_f32 v[76:77], v[76:77], v[86:87] op_sel_hi:[1,0]
	v_pk_mul_f32 v[78:79], v[242:243], v[78:79]
	v_pk_mul_f32 v[82:83], v[246:247], v[74:75]
	v_pk_mul_f32 v[74:75], v[244:245], v[72:73]
	v_pk_mul_f32 v[76:77], v[240:241], v[76:77]
	s_nop 0
	v_cvt_pk_bf16_f32 v72, v76, v77
	v_cvt_pk_bf16_f32 v73, v78, v79
	v_cvt_pk_bf16_f32 v74, v74, v75
	v_cvt_pk_bf16_f32 v75, v82, v83
	ds_read_b32 v78, v209 offset:8896
	v_lshl_add_u64 v[76:77], s[10:11], 0, v[90:91]
	global_store_dwordx4 v[76:77], v[72:75], off sc1
	s_nop 1
	v_lshlrev_b64 v[72:73], 10, v[136:137]
	v_lshl_add_u64 v[82:83], v[72:73], 0, v[200:201]
	v_cvt_pk_bf16_f32 v74, v68, v69
	v_lshlrev_b64 v[82:83], 1, v[82:83]
	s_waitcnt lgkmcnt(0)
	v_pk_mul_f32 v[68:69], v[68:69], v[78:79] op_sel_hi:[1,0]
	v_cvt_pk_bf16_f32 v75, v70, v71
	v_cvt_pk_bf16_f32 v76, v64, v65
	v_cvt_pk_bf16_f32 v77, v66, v67
	v_lshl_add_u64 v[84:85], s[8:9], 0, v[82:83]
	v_pk_mul_f32 v[68:69], v[240:241], v[68:69]
	v_pk_mul_f32 v[66:67], v[66:67], v[78:79] op_sel_hi:[1,0]
	v_pk_mul_f32 v[64:65], v[64:65], v[78:79] op_sel_hi:[1,0]
	global_store_dwordx4 v[84:85], v[74:77], off
	v_pk_mul_f32 v[70:71], v[70:71], v[78:79] op_sel_hi:[1,0]
	v_or_b32_e32 v200, 0x80, v200
	v_pk_mul_f32 v[74:75], v[246:247], v[66:67]
	v_pk_mul_f32 v[66:67], v[244:245], v[64:65]
	v_cvt_pk_bf16_f32 v64, v68, v69
	v_lshl_add_u64 v[68:69], s[10:11], 0, v[82:83]
	v_pk_mul_f32 v[70:71], v[242:243], v[70:71]
	v_lshl_add_u64 v[82:83], v[144:145], 0, v[200:201]
	v_cvt_pk_bf16_f32 v65, v70, v71
	v_cvt_pk_bf16_f32 v66, v66, v67
	v_cvt_pk_bf16_f32 v67, v74, v75
	global_store_dwordx4 v[68:69], v[64:67], off sc1
	s_nop 0
	ds_read_b32 v78, v209 offset:8192
	v_cvt_pk_bf16_f32 v74, v60, v61
	v_lshlrev_b64 v[82:83], 1, v[82:83]
	v_cvt_pk_bf16_f32 v75, v62, v63
	v_cvt_pk_bf16_f32 v76, v56, v57
	s_waitcnt lgkmcnt(0)
	v_pk_mul_f32 v[60:61], v[60:61], v[78:79] op_sel_hi:[1,0]
	v_cvt_pk_bf16_f32 v77, v58, v59
	v_lshl_add_u64 v[84:85], s[8:9], 0, v[82:83]
	v_pk_mul_f32 v[58:59], v[58:59], v[78:79] op_sel_hi:[1,0]
	v_pk_mul_f32 v[56:57], v[56:57], v[78:79] op_sel_hi:[1,0]
	global_store_dwordx4 v[84:85], v[74:77], off
	v_pk_mul_f32 v[62:63], v[62:63], v[78:79] op_sel_hi:[1,0]
	v_pk_mul_f32 v[60:61], v[226:227], v[60:61]
	v_pk_mul_f32 v[74:75], v[232:233], v[58:59]
	v_pk_mul_f32 v[58:59], v[230:231], v[56:57]
	v_cvt_pk_bf16_f32 v56, v60, v61
	v_lshl_add_u64 v[60:61], s[10:11], 0, v[82:83]
	v_pk_mul_f32 v[62:63], v[228:229], v[62:63]
	s_nop 0
	v_cvt_pk_bf16_f32 v57, v62, v63
	v_cvt_pk_bf16_f32 v58, v58, v59
	v_cvt_pk_bf16_f32 v59, v74, v75
	global_store_dwordx4 v[60:61], v[56:59], off sc1
	ds_read_b32 v60, v209 offset:8256
	v_lshl_add_u64 v[62:63], v[150:151], 0, v[200:201]
	v_cvt_pk_bf16_f32 v56, v52, v53
	v_lshlrev_b64 v[62:63], 1, v[62:63]
	v_cvt_pk_bf16_f32 v57, v54, v55
	s_waitcnt lgkmcnt(0)
	v_pk_mul_f32 v[52:53], v[52:53], v[60:61] op_sel_hi:[1,0]
	v_cvt_pk_bf16_f32 v58, v48, v49
	v_cvt_pk_bf16_f32 v59, v50, v51
	v_lshl_add_u64 v[74:75], s[8:9], 0, v[62:63]
	v_pk_mul_f32 v[52:53], v[226:227], v[52:53]
	v_pk_mul_f32 v[50:51], v[50:51], v[60:61] op_sel_hi:[1,0]
	v_pk_mul_f32 v[48:49], v[48:49], v[60:61] op_sel_hi:[1,0]
	global_store_dwordx4 v[74:75], v[56:59], off
	v_pk_mul_f32 v[54:55], v[54:55], v[60:61] op_sel_hi:[1,0]
	s_nop 0
	v_pk_mul_f32 v[56:57], v[232:233], v[50:51]
	v_pk_mul_f32 v[50:51], v[230:231], v[48:49]
	v_cvt_pk_bf16_f32 v48, v52, v53
	v_lshl_add_u64 v[52:53], s[10:11], 0, v[62:63]
	v_pk_mul_f32 v[54:55], v[228:229], v[54:55]
	s_nop 0
	v_cvt_pk_bf16_f32 v49, v54, v55
	v_cvt_pk_bf16_f32 v50, v50, v51
	v_cvt_pk_bf16_f32 v51, v56, v57
	global_store_dwordx4 v[52:53], v[48:51], off sc1
	ds_read_b32 v52, v209 offset:8320
	v_lshl_add_u64 v[54:55], v[148:149], 0, v[200:201]
	v_cvt_pk_bf16_f32 v48, v44, v45
	v_lshlrev_b64 v[54:55], 1, v[54:55]
	v_cvt_pk_bf16_f32 v49, v46, v47
	s_waitcnt lgkmcnt(0)
	v_pk_mul_f32 v[44:45], v[44:45], v[52:53] op_sel_hi:[1,0]
	v_cvt_pk_bf16_f32 v50, v40, v41
	v_cvt_pk_bf16_f32 v51, v42, v43
	v_lshl_add_u64 v[56:57], s[8:9], 0, v[54:55]
	v_pk_mul_f32 v[44:45], v[226:227], v[44:45]
	v_pk_mul_f32 v[42:43], v[42:43], v[52:53] op_sel_hi:[1,0]
	v_pk_mul_f32 v[40:41], v[40:41], v[52:53] op_sel_hi:[1,0]
	global_store_dwordx4 v[56:57], v[48:51], off
	v_pk_mul_f32 v[46:47], v[46:47], v[52:53] op_sel_hi:[1,0]
	s_nop 0
	v_pk_mul_f32 v[48:49], v[232:233], v[42:43]
	v_pk_mul_f32 v[42:43], v[230:231], v[40:41]
	v_cvt_pk_bf16_f32 v40, v44, v45
	v_lshl_add_u64 v[44:45], s[10:11], 0, v[54:55]
	v_pk_mul_f32 v[46:47], v[228:229], v[46:47]
	s_nop 0
	v_cvt_pk_bf16_f32 v41, v46, v47
	v_cvt_pk_bf16_f32 v42, v42, v43
	v_cvt_pk_bf16_f32 v43, v48, v49
	global_store_dwordx4 v[44:45], v[40:43], off sc1
	ds_read_b32 v44, v209 offset:8384
	v_lshl_add_u64 v[46:47], v[146:147], 0, v[200:201]
	v_cvt_pk_bf16_f32 v40, v36, v37
	v_lshlrev_b64 v[46:47], 1, v[46:47]
	v_cvt_pk_bf16_f32 v41, v38, v39
	s_waitcnt lgkmcnt(0)
	v_pk_mul_f32 v[36:37], v[36:37], v[44:45] op_sel_hi:[1,0]
	v_cvt_pk_bf16_f32 v42, v32, v33
	v_cvt_pk_bf16_f32 v43, v34, v35
	v_lshl_add_u64 v[48:49], s[8:9], 0, v[46:47]
	v_pk_mul_f32 v[36:37], v[226:227], v[36:37]
	v_pk_mul_f32 v[34:35], v[34:35], v[44:45] op_sel_hi:[1,0]
	v_pk_mul_f32 v[32:33], v[32:33], v[44:45] op_sel_hi:[1,0]
	global_store_dwordx4 v[48:49], v[40:43], off
	v_pk_mul_f32 v[38:39], v[38:39], v[44:45] op_sel_hi:[1,0]
	s_nop 0
	v_pk_mul_f32 v[40:41], v[232:233], v[34:35]
	v_pk_mul_f32 v[34:35], v[230:231], v[32:33]
	v_cvt_pk_bf16_f32 v32, v36, v37
	v_lshl_add_u64 v[36:37], s[10:11], 0, v[46:47]
	v_pk_mul_f32 v[38:39], v[228:229], v[38:39]
	s_nop 0
	v_cvt_pk_bf16_f32 v33, v38, v39
	v_cvt_pk_bf16_f32 v34, v34, v35
	v_cvt_pk_bf16_f32 v35, v40, v41
	global_store_dwordx4 v[36:37], v[32:35], off sc1
	ds_read_b32 v36, v209 offset:8704
	v_lshl_add_u64 v[38:39], v[96:97], 0, v[200:201]
	v_cvt_pk_bf16_f32 v32, v28, v29
	v_lshlrev_b64 v[38:39], 1, v[38:39]
	v_cvt_pk_bf16_f32 v33, v30, v31
	s_waitcnt lgkmcnt(0)
	v_pk_mul_f32 v[28:29], v[28:29], v[36:37] op_sel_hi:[1,0]
	v_cvt_pk_bf16_f32 v34, v24, v25
	v_cvt_pk_bf16_f32 v35, v26, v27
	v_lshl_add_u64 v[40:41], s[8:9], 0, v[38:39]
	v_pk_mul_f32 v[28:29], v[226:227], v[28:29]
	v_pk_mul_f32 v[26:27], v[26:27], v[36:37] op_sel_hi:[1,0]
	v_pk_mul_f32 v[24:25], v[24:25], v[36:37] op_sel_hi:[1,0]
	global_store_dwordx4 v[40:41], v[32:35], off
	v_pk_mul_f32 v[30:31], v[30:31], v[36:37] op_sel_hi:[1,0]
	s_nop 0
	v_pk_mul_f32 v[32:33], v[232:233], v[26:27]
	v_pk_mul_f32 v[26:27], v[230:231], v[24:25]
	v_cvt_pk_bf16_f32 v24, v28, v29
	v_lshl_add_u64 v[28:29], s[10:11], 0, v[38:39]
	v_pk_mul_f32 v[30:31], v[228:229], v[30:31]
	s_nop 0
	v_cvt_pk_bf16_f32 v25, v30, v31
	v_cvt_pk_bf16_f32 v26, v26, v27
	v_cvt_pk_bf16_f32 v27, v32, v33
	global_store_dwordx4 v[28:29], v[24:27], off sc1
	ds_read_b32 v28, v209 offset:8768
	v_lshl_add_u64 v[30:31], v[88:89], 0, v[200:201]
	v_cvt_pk_bf16_f32 v24, v20, v21
	v_lshlrev_b64 v[30:31], 1, v[30:31]
	v_cvt_pk_bf16_f32 v25, v22, v23
	s_waitcnt lgkmcnt(0)
	v_pk_mul_f32 v[20:21], v[20:21], v[28:29] op_sel_hi:[1,0]
	v_cvt_pk_bf16_f32 v26, v16, v17
	v_cvt_pk_bf16_f32 v27, v18, v19
	v_lshl_add_u64 v[32:33], s[8:9], 0, v[30:31]
	v_pk_mul_f32 v[20:21], v[226:227], v[20:21]
	v_pk_mul_f32 v[18:19], v[18:19], v[28:29] op_sel_hi:[1,0]
	v_pk_mul_f32 v[16:17], v[16:17], v[28:29] op_sel_hi:[1,0]
	global_store_dwordx4 v[32:33], v[24:27], off
	v_pk_mul_f32 v[22:23], v[22:23], v[28:29] op_sel_hi:[1,0]
	s_nop 0
	v_pk_mul_f32 v[24:25], v[232:233], v[18:19]
	v_pk_mul_f32 v[18:19], v[230:231], v[16:17]
	v_cvt_pk_bf16_f32 v16, v20, v21
	v_lshl_add_u64 v[20:21], s[10:11], 0, v[30:31]
	v_pk_mul_f32 v[22:23], v[228:229], v[22:23]
	s_nop 0
	v_cvt_pk_bf16_f32 v17, v22, v23
	v_cvt_pk_bf16_f32 v18, v18, v19
	v_cvt_pk_bf16_f32 v19, v24, v25
	global_store_dwordx4 v[20:21], v[16:19], off sc1
	ds_read_b32 v20, v209 offset:8832
	v_lshl_add_u64 v[22:23], v[80:81], 0, v[200:201]
	v_cvt_pk_bf16_f32 v16, v12, v13
	v_lshlrev_b64 v[22:23], 1, v[22:23]
	v_cvt_pk_bf16_f32 v17, v14, v15
	s_waitcnt lgkmcnt(0)
	v_pk_mul_f32 v[12:13], v[12:13], v[20:21] op_sel_hi:[1,0]
	v_cvt_pk_bf16_f32 v18, v8, v9
	v_cvt_pk_bf16_f32 v19, v10, v11
	v_lshl_add_u64 v[24:25], s[8:9], 0, v[22:23]
	v_pk_mul_f32 v[12:13], v[226:227], v[12:13]
	v_pk_mul_f32 v[10:11], v[10:11], v[20:21] op_sel_hi:[1,0]
	v_pk_mul_f32 v[8:9], v[8:9], v[20:21] op_sel_hi:[1,0]
	global_store_dwordx4 v[24:25], v[16:19], off
	v_pk_mul_f32 v[14:15], v[14:15], v[20:21] op_sel_hi:[1,0]
	s_nop 0
	v_pk_mul_f32 v[16:17], v[232:233], v[10:11]
	v_pk_mul_f32 v[10:11], v[230:231], v[8:9]
	v_cvt_pk_bf16_f32 v8, v12, v13
	v_lshl_add_u64 v[12:13], s[10:11], 0, v[22:23]
	v_pk_mul_f32 v[14:15], v[228:229], v[14:15]
	s_nop 0
	v_cvt_pk_bf16_f32 v9, v14, v15
	v_cvt_pk_bf16_f32 v10, v10, v11
	v_cvt_pk_bf16_f32 v11, v16, v17
	global_store_dwordx4 v[12:13], v[8:11], off sc1
	ds_read_b32 v12, v209 offset:8896
	v_lshl_add_u64 v[14:15], v[72:73], 0, v[200:201]
	v_cvt_pk_bf16_f32 v8, v4, v5
	v_lshlrev_b64 v[14:15], 1, v[14:15]
	v_cvt_pk_bf16_f32 v9, v6, v7
	s_waitcnt lgkmcnt(0)
	v_pk_mul_f32 v[4:5], v[4:5], v[12:13] op_sel_hi:[1,0]
	v_cvt_pk_bf16_f32 v10, v0, v1
	v_cvt_pk_bf16_f32 v11, v2, v3
	v_lshl_add_u64 v[16:17], s[8:9], 0, v[14:15]
	v_pk_mul_f32 v[4:5], v[226:227], v[4:5]
	v_pk_mul_f32 v[2:3], v[2:3], v[12:13] op_sel_hi:[1,0]
	v_pk_mul_f32 v[0:1], v[0:1], v[12:13] op_sel_hi:[1,0]
	global_store_dwordx4 v[16:17], v[8:11], off
	v_pk_mul_f32 v[6:7], v[6:7], v[12:13] op_sel_hi:[1,0]
	s_nop 0
	v_pk_mul_f32 v[8:9], v[232:233], v[2:3]
	v_pk_mul_f32 v[2:3], v[230:231], v[0:1]
	v_cvt_pk_bf16_f32 v0, v4, v5
	v_lshl_add_u64 v[4:5], s[10:11], 0, v[14:15]
	v_pk_mul_f32 v[6:7], v[228:229], v[6:7]
	s_nop 0
	v_cvt_pk_bf16_f32 v1, v6, v7
	v_cvt_pk_bf16_f32 v2, v2, v3
	v_cvt_pk_bf16_f32 v3, v8, v9
	global_store_dwordx4 v[4:5], v[0:3], off sc1
